# P0 streaming f32 input loads marked sc1 nt instead of nt (on top of aligned loop heads)
# baseline (speedup 1.0000x reference)
; #define LAS __attribute__((address_space(3)))
; __device__ __forceinline__ void tr_item(const float* W, const float* nw, int K, int N, bf16* WT, int k0, int n0, int drow0, LAS float* scr, int lane) {
;     { const int r = lane >> 3, c4 = lane & 7; f32x4 v[8];
; #pragma unroll
;       for (int i = 0; i < 8; ++i) v[i] = *(const f32x4*)(W + (size_t)(k0 + 8 * i + r) * N + n0 + 4 * c4);
; #pragma unroll
;       for (int i = 0; i < 8; ++i) { LAS float* d = scr + (8 * i + r) * 33 + 4 * c4; const float s = nw ? nw[k0 + 8 * i + r] : 1.f; d[0] = v[i].x * s; d[1] = v[i].y * s; d[2] = v[i].z * s; d[3] = v[i].w * s; } }
;     asm volatile("s_waitcnt lgkmcnt(0)" ::: "memory");
.LBB0_25:
	s_lshl_b32 s8, s11, 6
	v_or_b32_e32 v40, s8, v224
	s_ashr_i32 s11, s10, 31
	v_lshl_add_u64 v[2:3], s[10:11], 2, v[36:37]
	v_or_b32_e32 v6, 8, v40
	v_mad_i64_i32 v[4:5], s[10:11], v40, s21, v[2:3]
	v_mad_i64_i32 v[6:7], s[10:11], v6, s21, v[2:3]
	global_load_dwordx4 v[30:33], v[4:5], off sc1 nt
	global_load_dwordx4 v[26:29], v[6:7], off sc1 nt
	v_or_b32_e32 v4, 16, v40
	v_or_b32_e32 v6, 24, v40
	v_mad_i64_i32 v[4:5], s[10:11], v4, s21, v[2:3]
	v_mad_i64_i32 v[6:7], s[10:11], v6, s21, v[2:3]
	global_load_dwordx4 v[22:25], v[4:5], off sc1 nt
	global_load_dwordx4 v[18:21], v[6:7], off sc1 nt
	v_or_b32_e32 v4, 32, v40
	v_or_b32_e32 v6, 40, v40
	v_mad_i64_i32 v[4:5], s[10:11], v4, s21, v[2:3]
	v_mad_i64_i32 v[6:7], s[10:11], v6, s21, v[2:3]
	global_load_dwordx4 v[14:17], v[4:5], off sc1 nt
	global_load_dwordx4 v[10:13], v[6:7], off sc1 nt
	v_or_b32_e32 v4, 48, v40
	v_or_b32_e32 v6, 56, v40
	v_mad_i64_i32 v[4:5], s[10:11], v4, s21, v[2:3]
	v_mad_i64_i32 v[2:3], s[10:11], v6, s21, v[2:3]
	global_load_dwordx4 v[6:9], v[4:5], off sc1 nt
	s_nop 0
	global_load_dwordx4 v[2:5], v[2:3], off sc1 nt
	v_ashrrev_i32_e32 v41, 31, v40
	v_lshl_add_u64 v[40:41], v[40:41], 2, s[18:19]
	global_load_dword v245, v[40:41], off
	global_load_dword v246, v[40:41], off offset:32
	global_load_dword v247, v[40:41], off offset:64
	global_load_dword v248, v[40:41], off offset:96
	global_load_dword v249, v[40:41], off offset:128
	global_load_dword v251, v[40:41], off offset:160
	global_load_dword v252, v[40:41], off offset:192
	global_load_dword v253, v[40:41], off offset:224
	s_waitcnt vmcnt(0)
	v_mul_f32_e32 v30, v245, v30
	v_mul_f32_e32 v31, v245, v31
	v_mul_f32_e32 v32, v245, v32
	v_mul_f32_e32 v33, v245, v33
	v_mul_f32_e32 v26, v246, v26
	v_mul_f32_e32 v27, v246, v27
	v_mul_f32_e32 v28, v246, v28
	v_mul_f32_e32 v29, v246, v29
	v_mul_f32_e32 v22, v247, v22
	v_mul_f32_e32 v23, v247, v23
	v_mul_f32_e32 v24, v247, v24
	v_mul_f32_e32 v25, v247, v25
	v_mul_f32_e32 v18, v248, v18
	v_mul_f32_e32 v19, v248, v19
	v_mul_f32_e32 v20, v248, v20
	v_mul_f32_e32 v21, v248, v21
	v_mul_f32_e32 v14, v249, v14
	v_mul_f32_e32 v15, v249, v15
	v_mul_f32_e32 v16, v249, v16
	v_mul_f32_e32 v17, v249, v17
	v_mul_f32_e32 v10, v251, v10
	v_mul_f32_e32 v11, v251, v11
	v_mul_f32_e32 v12, v251, v12
	v_mul_f32_e32 v13, v251, v13
	v_mul_f32_e32 v6, v252, v6
	v_mul_f32_e32 v7, v252, v7
	v_mul_f32_e32 v8, v252, v8
	v_mul_f32_e32 v9, v252, v9
	v_mul_f32_e32 v2, v253, v2
	v_mul_f32_e32 v3, v253, v3
	v_mul_f32_e32 v4, v253, v4
	v_mul_f32_e32 v5, v253, v5
	ds_write2_b32 v46, v30, v31 offset1:1
	ds_write2_b32 v46, v32, v33 offset0:2 offset1:3
	v_add_u32_e32 v254, 0x420, v46
	ds_write2_b32 v254, v26, v27 offset1:1
	ds_write2_b32 v254, v28, v29 offset0:2 offset1:3
	v_add_u32_e32 v254, 0x840, v46
	ds_write2_b32 v254, v22, v23 offset1:1
	ds_write2_b32 v254, v24, v25 offset0:2 offset1:3
	v_add_u32_e32 v254, 0xc60, v46
	ds_write2_b32 v254, v18, v19 offset1:1
	ds_write2_b32 v254, v20, v21 offset0:2 offset1:3
	v_add_u32_e32 v254, 0x1080, v46
	ds_write2_b32 v254, v14, v15 offset1:1
	ds_write2_b32 v254, v16, v17 offset0:2 offset1:3
	v_add_u32_e32 v254, 0x14a0, v46
	ds_write2_b32 v254, v10, v11 offset1:1
	ds_write2_b32 v254, v12, v13 offset0:2 offset1:3
	v_add_u32_e32 v254, 0x18c0, v46
	ds_write2_b32 v254, v6, v7 offset1:1
	ds_write2_b32 v254, v8, v9 offset0:2 offset1:3
	v_add_u32_e32 v254, 0x1ce0, v46
	ds_write2_b32 v254, v2, v3 offset1:1
	ds_write2_b32 v254, v4, v5 offset0:2 offset1:3
	s_branch .LBB0_20

; #define LAS __attribute__((address_space(3)))
; __device__ __forceinline__ unsigned pkbf(float lo, float hi) { const f32x2_m v = {lo, hi}; const bf16x2_m b = __builtin_convertvector(v, bf16x2_m); return __builtin_bit_cast(unsigned, b); }
; __device__ __forceinline__ void tr_item(const float* W, const float* nw, int K, int N, bf16* WT, int k0, int n0, int drow0, LAS float* scr, int lane) {
;     { const int r = lane >> 3, c4 = lane & 7; f32x4 v[8];
; #pragma unroll
;       for (int i = 0; i < 8; ++i) v[i] = *(const f32x4*)(W + (size_t)(k0 + 8 * i + r) * N + n0 + 4 * c4);
; #pragma unroll
;       for (int i = 0; i < 8; ++i) { LAS float* d = scr + (8 * i + r) * 33 + 4 * c4; const float s = nw ? nw[k0 + 8 * i + r] : 1.f; d[0] = v[i].x * s; d[1] = v[i].y * s; d[2] = v[i].z * s; d[3] = v[i].w * s; } }
;     asm volatile("s_waitcnt lgkmcnt(0)" ::: "memory");
;     const int c = lane & 7;
; #pragma unroll
;     for (int j = 0; j < 4; ++j) { const int n = (lane >> 3) + 8 * j; const LAS float* s = scr + (8 * c) * 33 + n;
;         v4u o; o.x = pkbf(s[0 * 33], s[1 * 33]); o.y = pkbf(s[2 * 33], s[3 * 33]); o.z = pkbf(s[4 * 33], s[5 * 33]); o.w = pkbf(s[6 * 33], s[7 * 33]);
;         *(v4u*)(WT + (size_t)(drow0 + n) * K + k0 + 8 * c) = o; }
;     asm volatile("s_waitcnt lgkmcnt(0)" ::: "memory");
; }
; template <int MODE> __device__ __forceinline__ void conv_mat(const float* W, const float* nw, int K, int N, bf16* WT, LAS float* scr, int gw, int NGW, int lane) {
;     const int nblk = N / 32, nitems = (K / 64) * nblk;
;     for (int it = gw; it < nitems; it += NGW) { const int kb = it / nblk, nb = it % nblk, n0 = 32 * nb; int d = n0;
;         if (MODE == 1) { d = (n0 < DFF) ? 256 * (n0 / 128) + (n0 % 128) : 256 * ((n0 - DFF) / 128) + 128 + ((n0 - DFF) % 128); }
;         tr_item(W, nw, K, N, WT, 64 * kb, n0, d, scr, lane); }
.LBB0_35:
	s_ashr_i32 s4, s9, 31
	s_lshr_b32 s4, s4, 26
	s_add_i32 s4, s9, s4
	s_ashr_i32 s10, s4, 6
	s_andn2_b32 s4, s4, 63
	s_lshl_b32 s5, s10, 11
	v_or_b32_e32 v22, s4, v224
	s_sub_i32 s14, s3, s5
	v_ashrrev_i32_e32 v23, 31, v22
	v_or_b32_e32 v24, 8, v22
	v_or_b32_e32 v26, 16, v22
	v_or_b32_e32 v28, 24, v22
	v_or_b32_e32 v30, 32, v22
	v_or_b32_e32 v32, 40, v22
	v_or_b32_e32 v36, 48, v22
	v_or_b32_e32 v38, 56, v22
	s_ashr_i32 s15, s14, 31
	v_lshlrev_b64 v[22:23], 13, v[22:23]
	v_ashrrev_i32_e32 v25, 31, v24
	v_ashrrev_i32_e32 v27, 31, v26
	v_ashrrev_i32_e32 v29, 31, v28
	v_ashrrev_i32_e32 v31, 31, v30
	v_ashrrev_i32_e32 v33, 31, v32
	v_ashrrev_i32_e32 v37, 31, v36
	v_ashrrev_i32_e32 v39, 31, v38
	v_lshl_add_u64 v[40:41], s[14:15], 2, v[2:3]
	v_lshlrev_b64 v[24:25], 13, v[24:25]
	v_lshlrev_b64 v[26:27], 13, v[26:27]
	v_lshlrev_b64 v[28:29], 13, v[28:29]
	v_lshlrev_b64 v[30:31], 13, v[30:31]
	v_lshlrev_b64 v[32:33], 13, v[32:33]
	v_lshlrev_b64 v[36:37], 13, v[36:37]
	v_lshlrev_b64 v[38:39], 13, v[38:39]
	v_lshl_add_u64 v[56:57], v[40:41], 0, v[22:23]
	v_lshl_add_u64 v[58:59], v[40:41], 0, v[24:25]
	v_lshl_add_u64 v[60:61], v[40:41], 0, v[26:27]
	v_lshl_add_u64 v[62:63], v[40:41], 0, v[28:29]
	v_lshl_add_u64 v[64:65], v[40:41], 0, v[30:31]
	v_lshl_add_u64 v[66:67], v[40:41], 0, v[32:33]
	v_lshl_add_u64 v[68:69], v[40:41], 0, v[36:37]
	v_lshl_add_u64 v[70:71], v[40:41], 0, v[38:39]
	global_load_dwordx4 v[22:25], v[56:57], off sc1 nt
	global_load_dwordx4 v[26:29], v[58:59], off sc1 nt
	global_load_dwordx4 v[30:33], v[60:61], off sc1 nt
	global_load_dwordx4 v[36:39], v[62:63], off sc1 nt
	global_load_dwordx4 v[40:43], v[64:65], off sc1 nt
	global_load_dwordx4 v[44:47], v[66:67], off sc1 nt
	global_load_dwordx4 v[48:51], v[68:69], off sc1 nt
	global_load_dwordx4 v[52:55], v[70:71], off sc1 nt
	s_mul_i32 s10, s10, 0xff500000
	v_add_u32_e32 v58, s10, v6
	s_ashr_i32 s5, s4, 31
	v_add_u32_e32 v60, 0xb000, v58
	v_add_u32_e32 v62, 0x16000, v58
	v_add_u32_e32 v64, 0x21000, v58
	v_lshl_add_u64 v[56:57], s[4:5], 1, v[4:5]
	v_ashrrev_i32_e32 v59, 31, v58
	v_ashrrev_i32_e32 v61, 31, v60
	v_ashrrev_i32_e32 v63, 31, v62
	v_ashrrev_i32_e32 v65, 31, v64
	v_lshl_add_u64 v[58:59], v[58:59], 1, v[56:57]
	v_lshl_add_u64 v[60:61], v[60:61], 1, v[56:57]
	v_lshl_add_u64 v[62:63], v[62:63], 1, v[56:57]
	v_lshl_add_u64 v[56:57], v[64:65], 1, v[56:57]
	s_add_i32 s9, s9, s64
	s_add_i32 s3, s3, s8
	s_cmpk_lt_i32 s9, 0x1600
	v_add_u32_e32 v6, s11, v6
	s_waitcnt vmcnt(7)
	ds_write2_b32 v7, v22, v23 offset1:1
	ds_write2_b32 v7, v24, v25 offset0:2 offset1:3
	s_waitcnt vmcnt(6)
	ds_write2_b32 v8, v26, v27 offset1:1
	ds_write2_b32 v9, v28, v29 offset1:1
	s_waitcnt vmcnt(5)
	ds_write2_b32 v10, v30, v31 offset1:1
	ds_write2_b32 v11, v32, v33 offset1:1
	s_waitcnt vmcnt(4)
	ds_write2_b32 v12, v36, v37 offset1:1
	ds_write2_b32 v13, v38, v39 offset1:1
	s_waitcnt vmcnt(3)
	ds_write2_b32 v14, v40, v41 offset1:1
	ds_write2_b32 v15, v42, v43 offset1:1
	s_waitcnt vmcnt(2)
	ds_write2_b32 v16, v44, v45 offset1:1
	ds_write2_b32 v17, v46, v47 offset1:1
	s_waitcnt vmcnt(1)
	ds_write2_b32 v18, v48, v49 offset1:1
	ds_write2_b32 v19, v50, v51 offset1:1
	s_waitcnt vmcnt(0)
	ds_write2_b32 v20, v52, v53 offset1:1
	ds_write2_b32 v21, v54, v55 offset1:1
	s_waitcnt lgkmcnt(0)
	ds_read2_b32 v[24:25], v1 offset0:33 offset1:41
	ds_read2_b32 v[26:27], v1 offset1:8
	ds_read2_b32 v[28:29], v1 offset0:66 offset1:74
	ds_read2_b32 v[30:31], v1 offset0:99 offset1:107
	ds_read2_b32 v[32:33], v1 offset0:132 offset1:140
	ds_read2_b32 v[36:37], v1 offset0:165 offset1:173
	ds_read2_b32 v[38:39], v1 offset0:198 offset1:206
	ds_read2_b32 v[40:41], v1 offset0:231 offset1:239
	ds_read2_b32 v[42:43], v1 offset0:49 offset1:57
	ds_read2_b32 v[44:45], v1 offset0:16 offset1:24
	ds_read2_b32 v[46:47], v1 offset0:82 offset1:90
	ds_read2_b32 v[48:49], v1 offset0:115 offset1:123
	ds_read2_b32 v[50:51], v1 offset0:148 offset1:156
	ds_read2_b32 v[52:53], v1 offset0:181 offset1:189
	ds_read2_b32 v[54:55], v1 offset0:214 offset1:222
	ds_read2_b32 v[64:65], v1 offset0:247 offset1:255
	s_waitcnt lgkmcnt(14)
	v_cvt_pk_bf16_f32 v22, v26, v24
	s_waitcnt lgkmcnt(12)
	v_cvt_pk_bf16_f32 v23, v28, v30
	v_cvt_pk_bf16_f32 v26, v27, v25
	s_waitcnt lgkmcnt(10)
	v_cvt_pk_bf16_f32 v24, v32, v36
	s_waitcnt lgkmcnt(8)
	v_cvt_pk_bf16_f32 v25, v38, v40
	v_cvt_pk_bf16_f32 v27, v29, v31
	v_cvt_pk_bf16_f32 v28, v33, v37
	v_cvt_pk_bf16_f32 v29, v39, v41
	s_waitcnt lgkmcnt(6)
	v_cvt_pk_bf16_f32 v30, v44, v42
	s_waitcnt lgkmcnt(4)
	v_cvt_pk_bf16_f32 v31, v46, v48
	s_waitcnt lgkmcnt(2)
	v_cvt_pk_bf16_f32 v32, v50, v52
	s_waitcnt lgkmcnt(0)
	v_cvt_pk_bf16_f32 v33, v54, v64
	v_cvt_pk_bf16_f32 v36, v45, v43
	v_cvt_pk_bf16_f32 v37, v47, v49
	v_cvt_pk_bf16_f32 v38, v51, v53
	v_cvt_pk_bf16_f32 v39, v55, v65
	global_store_dwordx4 v[58:59], v[22:25], off
	global_store_dwordx4 v[60:61], v[26:29], off
	global_store_dwordx4 v[62:63], v[30:33], off
	global_store_dwordx4 v[56:57], v[36:39], off
	s_waitcnt lgkmcnt(0)
	s_cbranch_scc1 .LBB0_35

; #define LAS __attribute__((address_space(3)))
; __device__ __forceinline__ void tr_item(const float* W, const float* nw, int K, int N, bf16* WT, int k0, int n0, int drow0, LAS float* scr, int lane) {
;     { const int r = lane >> 3, c4 = lane & 7; f32x4 v[8];
; #pragma unroll
;       for (int i = 0; i < 8; ++i) v[i] = *(const f32x4*)(W + (size_t)(k0 + 8 * i + r) * N + n0 + 4 * c4);
; #pragma unroll
;       for (int i = 0; i < 8; ++i) { LAS float* d = scr + (8 * i + r) * 33 + 4 * c4; const float s = nw ? nw[k0 + 8 * i + r] : 1.f; d[0] = v[i].x * s; d[1] = v[i].y * s; d[2] = v[i].z * s; d[3] = v[i].w * s; } }
;     asm volatile("s_waitcnt lgkmcnt(0)" ::: "memory");
.LBB0_39:
	s_mul_hi_i32 s4, s14, 0x2e8ba2e9
	s_lshr_b32 s5, s4, 31
	s_ashr_i32 s4, s4, 6
	s_add_i32 s5, s4, s5
	s_mul_i32 s4, s5, 0xffffd400
	s_add_i32 s4, s3, s4
	s_lshl_b32 s8, s5, 6
	v_or_b32_e32 v40, s8, v224
	s_ashr_i32 s5, s4, 31
	v_lshl_add_u64 v[2:3], s[4:5], 2, v[36:37]
	v_or_b32_e32 v6, 8, v40
	v_mad_i64_i32 v[4:5], s[20:21], v40, s11, v[2:3]
	v_mad_i64_i32 v[6:7], s[20:21], v6, s11, v[2:3]
	global_load_dwordx4 v[30:33], v[4:5], off sc1 nt
	global_load_dwordx4 v[26:29], v[6:7], off sc1 nt
	v_or_b32_e32 v4, 16, v40
	v_or_b32_e32 v6, 24, v40
	v_mad_i64_i32 v[4:5], s[20:21], v4, s11, v[2:3]
	v_mad_i64_i32 v[6:7], s[20:21], v6, s11, v[2:3]
	global_load_dwordx4 v[22:25], v[4:5], off sc1 nt
	global_load_dwordx4 v[18:21], v[6:7], off sc1 nt
	v_or_b32_e32 v4, 32, v40
	v_or_b32_e32 v6, 40, v40
	v_mad_i64_i32 v[4:5], s[20:21], v4, s11, v[2:3]
	v_mad_i64_i32 v[6:7], s[20:21], v6, s11, v[2:3]
	global_load_dwordx4 v[14:17], v[4:5], off sc1 nt
	global_load_dwordx4 v[10:13], v[6:7], off sc1 nt
	v_or_b32_e32 v4, 48, v40
	v_or_b32_e32 v6, 56, v40
	v_mad_i64_i32 v[4:5], s[20:21], v4, s11, v[2:3]
	v_mad_i64_i32 v[2:3], s[20:21], v6, s11, v[2:3]
	global_load_dwordx4 v[6:9], v[4:5], off sc1 nt
	s_nop 0
	global_load_dwordx4 v[2:5], v[2:3], off sc1 nt
	v_ashrrev_i32_e32 v41, 31, v40
	v_lshl_add_u64 v[40:41], v[40:41], 2, s[24:25]
	global_load_dword v245, v[40:41], off
	global_load_dword v246, v[40:41], off offset:32
	global_load_dword v247, v[40:41], off offset:64
	global_load_dword v248, v[40:41], off offset:96
	global_load_dword v249, v[40:41], off offset:128
	global_load_dword v251, v[40:41], off offset:160
	global_load_dword v252, v[40:41], off offset:192
	global_load_dword v253, v[40:41], off offset:224
	s_waitcnt vmcnt(0)
	v_mul_f32_e32 v30, v245, v30
	v_mul_f32_e32 v31, v245, v31
	v_mul_f32_e32 v32, v245, v32
	v_mul_f32_e32 v33, v245, v33
	v_mul_f32_e32 v26, v246, v26
	v_mul_f32_e32 v27, v246, v27
	v_mul_f32_e32 v28, v246, v28
	v_mul_f32_e32 v29, v246, v29
	v_mul_f32_e32 v22, v247, v22
	v_mul_f32_e32 v23, v247, v23
	v_mul_f32_e32 v24, v247, v24
	v_mul_f32_e32 v25, v247, v25
	v_mul_f32_e32 v18, v248, v18
	v_mul_f32_e32 v19, v248, v19
	v_mul_f32_e32 v20, v248, v20
	v_mul_f32_e32 v21, v248, v21
	v_mul_f32_e32 v14, v249, v14
	v_mul_f32_e32 v15, v249, v15
	v_mul_f32_e32 v16, v249, v16
	v_mul_f32_e32 v17, v249, v17
	v_mul_f32_e32 v10, v251, v10
	v_mul_f32_e32 v11, v251, v11
	v_mul_f32_e32 v12, v251, v12
	v_mul_f32_e32 v13, v251, v13
	v_mul_f32_e32 v6, v252, v6
	v_mul_f32_e32 v7, v252, v7
	v_mul_f32_e32 v8, v252, v8
	v_mul_f32_e32 v9, v252, v9
	v_mul_f32_e32 v2, v253, v2
	v_mul_f32_e32 v3, v253, v3
	v_mul_f32_e32 v4, v253, v4
	v_mul_f32_e32 v5, v253, v5
	ds_write2_b32 v35, v30, v31 offset1:1
	ds_write2_b32 v35, v32, v33 offset0:2 offset1:3
	v_add_u32_e32 v254, 0x420, v35
	ds_write2_b32 v254, v26, v27 offset1:1
	ds_write2_b32 v254, v28, v29 offset0:2 offset1:3
	v_add_u32_e32 v254, 0x840, v35
	ds_write2_b32 v254, v22, v23 offset1:1
	ds_write2_b32 v254, v24, v25 offset0:2 offset1:3
	v_add_u32_e32 v254, 0xc60, v35
	ds_write2_b32 v254, v18, v19 offset1:1
	ds_write2_b32 v254, v20, v21 offset0:2 offset1:3
	v_add_u32_e32 v254, 0x1080, v35
	ds_write2_b32 v254, v14, v15 offset1:1
	ds_write2_b32 v254, v16, v17 offset0:2 offset1:3
	v_add_u32_e32 v254, 0x14a0, v35
	ds_write2_b32 v254, v10, v11 offset1:1
	ds_write2_b32 v254, v12, v13 offset0:2 offset1:3
	v_add_u32_e32 v254, 0x18c0, v35
	ds_write2_b32 v254, v6, v7 offset1:1
	ds_write2_b32 v254, v8, v9 offset0:2 offset1:3
	v_add_u32_e32 v254, 0x1ce0, v35
	ds_write2_b32 v254, v2, v3 offset1:1
	ds_write2_b32 v254, v4, v5 offset0:2 offset1:3
	s_branch .LBB0_38

; #define LAS __attribute__((address_space(3)))
; __device__ __forceinline__ unsigned pkbf(float lo, float hi) { const f32x2_m v = {lo, hi}; const bf16x2_m b = __builtin_convertvector(v, bf16x2_m); return __builtin_bit_cast(unsigned, b); }
; __device__ __forceinline__ void tr_item(const float* W, const float* nw, int K, int N, bf16* WT, int k0, int n0, int drow0, LAS float* scr, int lane) {
;     { const int r = lane >> 3, c4 = lane & 7; f32x4 v[8];
; #pragma unroll
;       for (int i = 0; i < 8; ++i) v[i] = *(const f32x4*)(W + (size_t)(k0 + 8 * i + r) * N + n0 + 4 * c4);
; #pragma unroll
;       for (int i = 0; i < 8; ++i) { LAS float* d = scr + (8 * i + r) * 33 + 4 * c4; const float s = nw ? nw[k0 + 8 * i + r] : 1.f; d[0] = v[i].x * s; d[1] = v[i].y * s; d[2] = v[i].z * s; d[3] = v[i].w * s; } }
;     asm volatile("s_waitcnt lgkmcnt(0)" ::: "memory");
;     const int c = lane & 7;
; #pragma unroll
;     for (int j = 0; j < 4; ++j) { const int n = (lane >> 3) + 8 * j; const LAS float* s = scr + (8 * c) * 33 + n;
;         v4u o; o.x = pkbf(s[0 * 33], s[1 * 33]); o.y = pkbf(s[2 * 33], s[3 * 33]); o.z = pkbf(s[4 * 33], s[5 * 33]); o.w = pkbf(s[6 * 33], s[7 * 33]);
;         *(v4u*)(WT + (size_t)(drow0 + n) * K + k0 + 8 * c) = o; }
;     asm volatile("s_waitcnt lgkmcnt(0)" ::: "memory");
; }
; template <int MODE> __device__ __forceinline__ void conv_mat(const float* W, const float* nw, int K, int N, bf16* WT, LAS float* scr, int gw, int NGW, int lane) {
;     const int nblk = N / 32, nitems = (K / 64) * nblk;
;     for (int it = gw; it < nitems; it += NGW) { const int kb = it / nblk, nb = it % nblk, n0 = 32 * nb; int d = n0;
;         if (MODE == 1) { d = (n0 < DFF) ? 256 * (n0 / 128) + (n0 % 128) : 256 * ((n0 - DFF) / 128) + 128 + ((n0 - DFF) % 128); }
;         tr_item(W, nw, K, N, WT, 64 * kb, n0, d, scr, lane); }
.LBB0_49:
	s_ashr_i32 s0, s8, 31
	s_lshr_b32 s0, s0, 26
	s_add_i32 s0, s8, s0
	s_lshl_b32 s1, s0, 5
	s_andn2_b32 s0, s0, 63
	s_and_b32 s1, s1, 0xfffff800
	v_or_b32_e32 v24, s0, v224
	s_sub_i32 s4, s7, s1
	v_or_b32_e32 v26, 8, v24
	v_or_b32_e32 v28, 16, v24
	v_or_b32_e32 v30, 24, v24
	v_or_b32_e32 v36, 40, v24
	v_or_b32_e32 v38, 48, v24
	v_or_b32_e32 v40, 56, v24
	v_ashrrev_i32_e32 v25, 31, v24
	v_or_b32_e32 v32, 32, v24
	s_ashr_i32 s5, s4, 31
	v_ashrrev_i32_e32 v27, 31, v26
	v_ashrrev_i32_e32 v29, 31, v28
	v_ashrrev_i32_e32 v31, 31, v30
	v_ashrrev_i32_e32 v37, 31, v36
	v_ashrrev_i32_e32 v39, 31, v38
	v_ashrrev_i32_e32 v41, 31, v40
	v_lshlrev_b64 v[24:25], 13, v[24:25]
	v_ashrrev_i32_e32 v33, 31, v32
	v_lshl_add_u64 v[42:43], s[4:5], 2, v[6:7]
	v_lshlrev_b64 v[26:27], 13, v[26:27]
	v_lshlrev_b64 v[28:29], 13, v[28:29]
	v_lshlrev_b64 v[30:31], 13, v[30:31]
	v_lshlrev_b64 v[36:37], 13, v[36:37]
	v_lshlrev_b64 v[38:39], 13, v[38:39]
	v_lshlrev_b64 v[40:41], 13, v[40:41]
	v_lshlrev_b64 v[32:33], 13, v[32:33]
	v_lshl_add_u64 v[24:25], v[42:43], 0, v[24:25]
	v_lshl_add_u64 v[44:45], v[42:43], 0, v[26:27]
	v_lshl_add_u64 v[46:47], v[42:43], 0, v[28:29]
	v_lshl_add_u64 v[48:49], v[42:43], 0, v[30:31]
	v_lshl_add_u64 v[50:51], v[42:43], 0, v[36:37]
	v_lshl_add_u64 v[52:53], v[42:43], 0, v[38:39]
	v_lshl_add_u64 v[56:57], v[42:43], 0, v[40:41]
	v_lshl_add_u64 v[32:33], v[42:43], 0, v[32:33]
	global_load_dwordx4 v[24:27], v[24:25], off sc1 nt
	s_nop 0
	global_load_dwordx4 v[28:31], v[44:45], off sc1 nt
	global_load_dwordx4 v[36:39], v[46:47], off sc1 nt
	global_load_dwordx4 v[40:43], v[48:49], off sc1 nt
	s_nop 0
	global_load_dwordx4 v[44:47], v[32:33], off sc1 nt
	s_nop 0
	global_load_dwordx4 v[48:51], v[50:51], off sc1 nt
	s_nop 0
	global_load_dwordx4 v[52:55], v[52:53], off sc1 nt
	s_nop 0
	global_load_dwordx4 v[56:59], v[56:57], off sc1 nt
	v_add_u32_e32 v60, s4, v224
	v_add_u32_e32 v62, 8, v60
	v_add_u32_e32 v64, 16, v60
	v_add_u32_e32 v66, 24, v60
	s_ashr_i32 s1, s0, 31
	v_ashrrev_i32_e32 v61, 31, v60
	v_ashrrev_i32_e32 v63, 31, v62
	v_ashrrev_i32_e32 v65, 31, v64
	v_ashrrev_i32_e32 v67, 31, v66
	v_lshl_add_u64 v[32:33], s[0:1], 1, v[8:9]
	v_lshlrev_b64 v[60:61], 11, v[60:61]
	v_lshlrev_b64 v[62:63], 11, v[62:63]
	v_lshlrev_b64 v[64:65], 11, v[64:65]
	v_lshlrev_b64 v[66:67], 11, v[66:67]
	v_lshl_add_u64 v[60:61], v[32:33], 0, v[60:61]
	v_lshl_add_u64 v[62:63], v[32:33], 0, v[62:63]
	v_lshl_add_u64 v[64:65], v[32:33], 0, v[64:65]
	v_lshl_add_u64 v[32:33], v[32:33], 0, v[66:67]
	s_add_i32 s8, s8, s64
	s_add_i32 s7, s7, s6
	s_cmpk_lt_i32 s8, 0x400
	s_waitcnt vmcnt(7)
	ds_write2_b32 v10, v24, v25 offset1:1
	ds_write2_b32 v10, v26, v27 offset0:2 offset1:3
	s_waitcnt vmcnt(6)
	ds_write2_b32 v3, v28, v29 offset1:1
	ds_write2_b32 v5, v30, v31 offset1:1
	s_waitcnt vmcnt(5)
	ds_write2_b32 v11, v36, v37 offset1:1
	ds_write2_b32 v12, v38, v39 offset1:1
	s_waitcnt vmcnt(4)
	ds_write2_b32 v13, v40, v41 offset1:1
	ds_write2_b32 v14, v42, v43 offset1:1
	s_waitcnt vmcnt(3)
	ds_write2_b32 v15, v44, v45 offset1:1
	ds_write2_b32 v16, v46, v47 offset1:1
	s_waitcnt vmcnt(2)
	ds_write2_b32 v17, v48, v49 offset1:1
	ds_write2_b32 v18, v50, v51 offset1:1
	s_waitcnt vmcnt(1)
	ds_write2_b32 v19, v52, v53 offset1:1
	ds_write2_b32 v20, v54, v55 offset1:1
	s_waitcnt vmcnt(0)
	ds_write2_b32 v21, v56, v57 offset1:1
	ds_write2_b32 v22, v58, v59 offset1:1
	s_waitcnt lgkmcnt(0)
	ds_read2_b32 v[28:29], v1 offset0:33 offset1:41
	ds_read2_b32 v[30:31], v1 offset1:8
	ds_read2_b32 v[36:37], v1 offset0:66 offset1:74
	ds_read2_b32 v[38:39], v1 offset0:99 offset1:107
	ds_read2_b32 v[40:41], v1 offset0:132 offset1:140
	ds_read2_b32 v[42:43], v1 offset0:165 offset1:173
	ds_read2_b32 v[44:45], v1 offset0:198 offset1:206
	ds_read2_b32 v[46:47], v1 offset0:231 offset1:239
	ds_read2_b32 v[48:49], v1 offset0:49 offset1:57
	ds_read2_b32 v[50:51], v1 offset0:16 offset1:24
	ds_read2_b32 v[52:53], v1 offset0:82 offset1:90
	ds_read2_b32 v[54:55], v1 offset0:115 offset1:123
	ds_read2_b32 v[56:57], v1 offset0:148 offset1:156
	ds_read2_b32 v[58:59], v1 offset0:181 offset1:189
	ds_read2_b32 v[66:67], v1 offset0:214 offset1:222
	ds_read2_b32 v[68:69], v1 offset0:247 offset1:255
	s_waitcnt lgkmcnt(14)
	v_cvt_pk_bf16_f32 v24, v30, v28
	s_waitcnt lgkmcnt(12)
	v_cvt_pk_bf16_f32 v25, v36, v38
	s_waitcnt lgkmcnt(10)
	v_cvt_pk_bf16_f32 v26, v40, v42
	s_waitcnt lgkmcnt(8)
	v_cvt_pk_bf16_f32 v27, v44, v46
	v_cvt_pk_bf16_f32 v28, v31, v29
	v_cvt_pk_bf16_f32 v29, v37, v39
	v_cvt_pk_bf16_f32 v30, v41, v43
	v_cvt_pk_bf16_f32 v31, v45, v47
	s_waitcnt lgkmcnt(6)
	v_cvt_pk_bf16_f32 v36, v50, v48
	s_waitcnt lgkmcnt(4)
	v_cvt_pk_bf16_f32 v37, v52, v54
	s_waitcnt lgkmcnt(2)
	v_cvt_pk_bf16_f32 v38, v56, v58
	s_waitcnt lgkmcnt(0)
	v_cvt_pk_bf16_f32 v39, v66, v68
	v_cvt_pk_bf16_f32 v40, v51, v49
	v_cvt_pk_bf16_f32 v41, v53, v55
	v_cvt_pk_bf16_f32 v42, v57, v59
	v_cvt_pk_bf16_f32 v43, v67, v69
	global_store_dwordx4 v[60:61], v[24:27], off
	global_store_dwordx4 v[62:63], v[28:31], off
	global_store_dwordx4 v[64:65], v[36:39], off
	global_store_dwordx4 v[32:33], v[40:43], off
	s_waitcnt lgkmcnt(0)
	s_cbranch_scc1 .LBB0_49
	v_readlane_b32 s36, v250, 12
	v_lshlrev_b32_e32 v6, 2, v2
	v_mov_b32_e32 v7, 0
	v_readlane_b32 s48, v250, 24
	v_readlane_b32 s49, v250, 25
	v_readlane_b32 s0, v250, 28
	v_readlane_b32 s1, v250, 29
	v_lshl_add_u64 v[2:3], s[48:49], 0, v[6:7]
	v_lshlrev_b32_e32 v6, 1, v4
	v_lshl_add_u64 v[4:5], s[0:1], 0, v[6:7]
	s_mov_b32 s7, s34
	v_readlane_b32 s37, v250, 13
	v_readlane_b32 s38, v250, 14
	v_readlane_b32 s39, v250, 15
	v_readlane_b32 s40, v250, 16
	v_readlane_b32 s41, v250, 17
	v_readlane_b32 s42, v250, 18
	v_readlane_b32 s43, v250, 19
	v_readlane_b32 s44, v250, 20
	v_readlane_b32 s45, v250, 21
	v_readlane_b32 s46, v250, 22
	v_readlane_b32 s47, v250, 23
	v_readlane_b32 s50, v250, 26
	v_readlane_b32 s51, v250, 27
; #define LAS __attribute__((address_space(3)))
; __device__ __forceinline__ unsigned pkbf(float lo, float hi) { const f32x2_m v = {lo, hi}; const bf16x2_m b = __builtin_convertvector(v, bf16x2_m); return __builtin_bit_cast(unsigned, b); }
; __device__ __forceinline__ void tr_item(const float* W, const float* nw, int K, int N, bf16* WT, int k0, int n0, int drow0, LAS float* scr, int lane) {
;     { const int r = lane >> 3, c4 = lane & 7; f32x4 v[8];
; #pragma unroll
;       for (int i = 0; i < 8; ++i) v[i] = *(const f32x4*)(W + (size_t)(k0 + 8 * i + r) * N + n0 + 4 * c4);
; #pragma unroll
;       for (int i = 0; i < 8; ++i) { LAS float* d = scr + (8 * i + r) * 33 + 4 * c4; const float s = nw ? nw[k0 + 8 * i + r] : 1.f; d[0] = v[i].x * s; d[1] = v[i].y * s; d[2] = v[i].z * s; d[3] = v[i].w * s; } }
;     asm volatile("s_waitcnt lgkmcnt(0)" ::: "memory");
;     const int c = lane & 7;
; #pragma unroll
;     for (int j = 0; j < 4; ++j) { const int n = (lane >> 3) + 8 * j; const LAS float* s = scr + (8 * c) * 33 + n;
;         v4u o; o.x = pkbf(s[0 * 33], s[1 * 33]); o.y = pkbf(s[2 * 33], s[3 * 33]); o.z = pkbf(s[4 * 33], s[5 * 33]); o.w = pkbf(s[6 * 33], s[7 * 33]);
;         *(v4u*)(WT + (size_t)(drow0 + n) * K + k0 + 8 * c) = o; }
;     asm volatile("s_waitcnt lgkmcnt(0)" ::: "memory");
; }
; template <int MODE> __device__ __forceinline__ void conv_mat(const float* W, const float* nw, int K, int N, bf16* WT, LAS float* scr, int gw, int NGW, int lane) {
;     const int nblk = N / 32, nitems = (K / 64) * nblk;
;     for (int it = gw; it < nitems; it += NGW) { const int kb = it / nblk, nb = it % nblk, n0 = 32 * nb; int d = n0;
;         if (MODE == 1) { d = (n0 < DFF) ? 256 * (n0 / 128) + (n0 % 128) : 256 * ((n0 - DFF) / 128) + 128 + ((n0 - DFF) % 128); }
;         tr_item(W, nw, K, N, WT, 64 * kb, n0, d, scr, lane); }
.LBB0_51:
	s_ashr_i32 s0, s7, 31
	s_lshr_b32 s0, s0, 26
	s_add_i32 s0, s7, s0
	s_lshl_b32 s1, s0, 5
	s_andn2_b32 s0, s0, 63
	s_and_b32 s1, s1, 0xfffff800
	v_or_b32_e32 v6, s0, v224
	s_sub_i32 s4, s3, s1
	v_or_b32_e32 v8, 8, v6
	v_or_b32_e32 v12, 16, v6
	v_or_b32_e32 v14, 24, v6
	v_or_b32_e32 v18, 40, v6
	v_or_b32_e32 v20, 48, v6
	v_or_b32_e32 v22, 56, v6
	v_ashrrev_i32_e32 v7, 31, v6
	v_or_b32_e32 v16, 32, v6
	s_ashr_i32 s5, s4, 31
	v_ashrrev_i32_e32 v9, 31, v8
	v_ashrrev_i32_e32 v13, 31, v12
	v_ashrrev_i32_e32 v15, 31, v14
	v_ashrrev_i32_e32 v19, 31, v18
	v_ashrrev_i32_e32 v21, 31, v20
	v_ashrrev_i32_e32 v23, 31, v22
	v_lshlrev_b64 v[6:7], 13, v[6:7]
	v_ashrrev_i32_e32 v17, 31, v16
	v_lshl_add_u64 v[24:25], s[4:5], 2, v[2:3]
	v_lshlrev_b64 v[8:9], 13, v[8:9]
	v_lshlrev_b64 v[12:13], 13, v[12:13]
	v_lshlrev_b64 v[14:15], 13, v[14:15]
	v_lshlrev_b64 v[18:19], 13, v[18:19]
	v_lshlrev_b64 v[20:21], 13, v[20:21]
	v_lshlrev_b64 v[22:23], 13, v[22:23]
	v_lshlrev_b64 v[16:17], 13, v[16:17]
	v_lshl_add_u64 v[6:7], v[24:25], 0, v[6:7]
	v_lshl_add_u64 v[26:27], v[24:25], 0, v[8:9]
	v_lshl_add_u64 v[28:29], v[24:25], 0, v[12:13]
	v_lshl_add_u64 v[30:31], v[24:25], 0, v[14:15]
	v_lshl_add_u64 v[36:37], v[24:25], 0, v[18:19]
	v_lshl_add_u64 v[38:39], v[24:25], 0, v[20:21]
	v_lshl_add_u64 v[40:41], v[24:25], 0, v[22:23]
	v_lshl_add_u64 v[32:33], v[24:25], 0, v[16:17]
	global_load_dwordx4 v[6:9], v[6:7], off sc1 nt
	s_nop 0
	global_load_dwordx4 v[12:15], v[26:27], off sc1 nt
	global_load_dwordx4 v[16:19], v[28:29], off sc1 nt
	global_load_dwordx4 v[20:23], v[30:31], off sc1 nt
	s_nop 0
	global_load_dwordx4 v[24:27], v[32:33], off sc1 nt
	global_load_dwordx4 v[28:31], v[36:37], off sc1 nt
	s_nop 0
	global_load_dwordx4 v[36:39], v[38:39], off sc1 nt
	s_nop 0
	global_load_dwordx4 v[40:43], v[40:41], off sc1 nt
	v_add_u32_e32 v44, s4, v224
	v_add_u32_e32 v46, 8, v44
	v_add_u32_e32 v48, 16, v44
	v_add_u32_e32 v50, 24, v44
	v_add_u32_e32 v11, 0x420, v10
	v_add_u32_e32 v35, 0x428, v10
	v_add_u32_e32 v52, 0x840, v10
	v_add_u32_e32 v53, 0x848, v10
	v_add_u32_e32 v54, 0xc60, v10
	v_add_u32_e32 v55, 0xc68, v10
	v_add_u32_e32 v56, 0x1080, v10
	v_add_u32_e32 v57, 0x1088, v10
	v_add_u32_e32 v58, 0x14a0, v10
	v_add_u32_e32 v59, 0x14a8, v10
	v_add_u32_e32 v60, 0x18c0, v10
	v_add_u32_e32 v61, 0x18c8, v10
	v_add_u32_e32 v62, 0x1ce0, v10
	v_add_u32_e32 v63, 0x1ce8, v10
	s_ashr_i32 s1, s0, 31
	v_ashrrev_i32_e32 v45, 31, v44
	v_ashrrev_i32_e32 v47, 31, v46
	v_ashrrev_i32_e32 v49, 31, v48
	v_ashrrev_i32_e32 v51, 31, v50
	v_lshl_add_u64 v[32:33], s[0:1], 1, v[4:5]
	v_lshlrev_b64 v[44:45], 11, v[44:45]
	v_lshlrev_b64 v[46:47], 11, v[46:47]
	v_lshlrev_b64 v[48:49], 11, v[48:49]
	v_lshlrev_b64 v[50:51], 11, v[50:51]
	v_lshl_add_u64 v[44:45], v[32:33], 0, v[44:45]
	v_lshl_add_u64 v[46:47], v[32:33], 0, v[46:47]
	v_lshl_add_u64 v[48:49], v[32:33], 0, v[48:49]
	v_lshl_add_u64 v[32:33], v[32:33], 0, v[50:51]
	s_add_i32 s7, s7, s64
	s_add_i32 s3, s3, s6
	s_cmpk_lt_i32 s7, 0x400
	s_waitcnt vmcnt(7)
	ds_write2_b32 v10, v6, v7 offset1:1
	ds_write2_b32 v10, v8, v9 offset0:2 offset1:3
	s_waitcnt vmcnt(6)
	ds_write2_b32 v11, v12, v13 offset1:1
	ds_write2_b32 v35, v14, v15 offset1:1
	s_waitcnt vmcnt(5)
	ds_write2_b32 v52, v16, v17 offset1:1
	ds_write2_b32 v53, v18, v19 offset1:1
	s_waitcnt vmcnt(4)
	ds_write2_b32 v54, v20, v21 offset1:1
	ds_write2_b32 v55, v22, v23 offset1:1
	s_waitcnt vmcnt(3)
	ds_write2_b32 v56, v24, v25 offset1:1
	ds_write2_b32 v57, v26, v27 offset1:1
	s_waitcnt vmcnt(2)
	ds_write2_b32 v58, v28, v29 offset1:1
	ds_write2_b32 v59, v30, v31 offset1:1
	s_waitcnt vmcnt(1)
	ds_write2_b32 v60, v36, v37 offset1:1
	ds_write2_b32 v61, v38, v39 offset1:1
	s_waitcnt vmcnt(0)
	ds_write2_b32 v62, v40, v41 offset1:1
	ds_write2_b32 v63, v42, v43 offset1:1
	s_waitcnt lgkmcnt(0)
	ds_read2_b32 v[12:13], v1 offset0:33 offset1:41
	ds_read2_b32 v[14:15], v1 offset1:8
	ds_read2_b32 v[16:17], v1 offset0:66 offset1:74
	ds_read2_b32 v[18:19], v1 offset0:99 offset1:107
	ds_read2_b32 v[20:21], v1 offset0:132 offset1:140
	ds_read2_b32 v[22:23], v1 offset0:165 offset1:173
	ds_read2_b32 v[24:25], v1 offset0:198 offset1:206
	ds_read2_b32 v[26:27], v1 offset0:231 offset1:239
	ds_read2_b32 v[28:29], v1 offset0:49 offset1:57
	ds_read2_b32 v[30:31], v1 offset0:16 offset1:24
	ds_read2_b32 v[36:37], v1 offset0:82 offset1:90
	ds_read2_b32 v[38:39], v1 offset0:115 offset1:123
	ds_read2_b32 v[40:41], v1 offset0:148 offset1:156
	ds_read2_b32 v[42:43], v1 offset0:181 offset1:189
	ds_read2_b32 v[50:51], v1 offset0:214 offset1:222
	ds_read2_b32 v[52:53], v1 offset0:247 offset1:255
	s_waitcnt lgkmcnt(14)
	v_cvt_pk_bf16_f32 v6, v14, v12
	s_waitcnt lgkmcnt(12)
	v_cvt_pk_bf16_f32 v7, v16, v18
	s_waitcnt lgkmcnt(10)
	v_cvt_pk_bf16_f32 v8, v20, v22
	s_waitcnt lgkmcnt(8)
	v_cvt_pk_bf16_f32 v9, v24, v26
	v_cvt_pk_bf16_f32 v12, v15, v13
	v_cvt_pk_bf16_f32 v13, v17, v19
	v_cvt_pk_bf16_f32 v14, v21, v23
	v_cvt_pk_bf16_f32 v15, v25, v27
	s_waitcnt lgkmcnt(6)
	v_cvt_pk_bf16_f32 v16, v30, v28
	s_waitcnt lgkmcnt(4)
	v_cvt_pk_bf16_f32 v17, v36, v38
	s_waitcnt lgkmcnt(2)
	v_cvt_pk_bf16_f32 v18, v40, v42
	s_waitcnt lgkmcnt(0)
	v_cvt_pk_bf16_f32 v19, v50, v52
	v_cvt_pk_bf16_f32 v20, v31, v29
	v_cvt_pk_bf16_f32 v21, v37, v39
	v_cvt_pk_bf16_f32 v22, v41, v43
	v_cvt_pk_bf16_f32 v23, v51, v53
	global_store_dwordx4 v[44:45], v[6:9], off
	global_store_dwordx4 v[46:47], v[12:15], off
	global_store_dwordx4 v[48:49], v[16:19], off
	global_store_dwordx4 v[32:33], v[20:23], off
	s_waitcnt lgkmcnt(0)
	s_cbranch_scc1 .LBB0_51

; #define LAS __attribute__((address_space(3)))
; __device__ __forceinline__ unsigned pkbf(float lo, float hi) { const f32x2_m v = {lo, hi}; const bf16x2_m b = __builtin_convertvector(v, bf16x2_m); return __builtin_bit_cast(unsigned, b); }
; __device__ __forceinline__ void tr_item(const float* W, const float* nw, int K, int N, bf16* WT, int k0, int n0, int drow0, LAS float* scr, int lane) {
;     { const int r = lane >> 3, c4 = lane & 7; f32x4 v[8];
; #pragma unroll
;       for (int i = 0; i < 8; ++i) v[i] = *(const f32x4*)(W + (size_t)(k0 + 8 * i + r) * N + n0 + 4 * c4);
; #pragma unroll
;       for (int i = 0; i < 8; ++i) { LAS float* d = scr + (8 * i + r) * 33 + 4 * c4; const float s = nw ? nw[k0 + 8 * i + r] : 1.f; d[0] = v[i].x * s; d[1] = v[i].y * s; d[2] = v[i].z * s; d[3] = v[i].w * s; } }
;     asm volatile("s_waitcnt lgkmcnt(0)" ::: "memory");
;     const int c = lane & 7;
; #pragma unroll
;     for (int j = 0; j < 4; ++j) { const int n = (lane >> 3) + 8 * j; const LAS float* s = scr + (8 * c) * 33 + n;
;         v4u o; o.x = pkbf(s[0 * 33], s[1 * 33]); o.y = pkbf(s[2 * 33], s[3 * 33]); o.z = pkbf(s[4 * 33], s[5 * 33]); o.w = pkbf(s[6 * 33], s[7 * 33]);
;         *(v4u*)(WT + (size_t)(drow0 + n) * K + k0 + 8 * c) = o; }
;     asm volatile("s_waitcnt lgkmcnt(0)" ::: "memory");
; }
; template <int MODE> __device__ __forceinline__ void conv_mat(const float* W, const float* nw, int K, int N, bf16* WT, LAS float* scr, int gw, int NGW, int lane) {
;     const int nblk = N / 32, nitems = (K / 64) * nblk;
;     for (int it = gw; it < nitems; it += NGW) { const int kb = it / nblk, nb = it % nblk, n0 = 32 * nb; int d = n0;
;         if (MODE == 1) { d = (n0 < DFF) ? 256 * (n0 / 128) + (n0 % 128) : 256 * ((n0 - DFF) / 128) + 128 + ((n0 - DFF) % 128); }
;         tr_item(W, nw, K, N, WT, 64 * kb, n0, d, scr, lane); }
.LBB0_54:
	s_ashr_i32 s0, s7, 31
	s_lshr_b32 s0, s0, 26
	s_add_i32 s0, s7, s0
	s_lshl_b32 s1, s0, 5
	s_andn2_b32 s0, s0, 63
	s_and_b32 s1, s1, 0xfffff800
	v_or_b32_e32 v22, s0, v224
	s_sub_i32 s4, s3, s1
	v_or_b32_e32 v24, 8, v22
	v_or_b32_e32 v26, 16, v22
	v_or_b32_e32 v28, 24, v22
	v_or_b32_e32 v30, 32, v22
	v_or_b32_e32 v32, 40, v22
	v_or_b32_e32 v36, 48, v22
	v_or_b32_e32 v38, 56, v22
	v_ashrrev_i32_e32 v23, 31, v22
	s_ashr_i32 s5, s4, 31
	v_ashrrev_i32_e32 v25, 31, v24
	v_ashrrev_i32_e32 v27, 31, v26
	v_ashrrev_i32_e32 v29, 31, v28
	v_ashrrev_i32_e32 v31, 31, v30
	v_ashrrev_i32_e32 v33, 31, v32
	v_ashrrev_i32_e32 v37, 31, v36
	v_ashrrev_i32_e32 v39, 31, v38
	v_lshlrev_b64 v[22:23], 13, v[22:23]
	v_lshl_add_u64 v[40:41], s[4:5], 2, v[2:3]
	v_lshlrev_b64 v[24:25], 13, v[24:25]
	v_lshlrev_b64 v[26:27], 13, v[26:27]
	v_lshlrev_b64 v[28:29], 13, v[28:29]
	v_lshlrev_b64 v[30:31], 13, v[30:31]
	v_lshlrev_b64 v[32:33], 13, v[32:33]
	v_lshlrev_b64 v[36:37], 13, v[36:37]
	v_lshlrev_b64 v[38:39], 13, v[38:39]
	v_lshl_add_u64 v[22:23], v[40:41], 0, v[22:23]
	v_lshl_add_u64 v[42:43], v[40:41], 0, v[24:25]
	v_lshl_add_u64 v[44:45], v[40:41], 0, v[26:27]
	v_lshl_add_u64 v[46:47], v[40:41], 0, v[28:29]
	v_lshl_add_u64 v[48:49], v[40:41], 0, v[30:31]
	v_lshl_add_u64 v[50:51], v[40:41], 0, v[32:33]
	v_lshl_add_u64 v[52:53], v[40:41], 0, v[36:37]
	v_lshl_add_u64 v[54:55], v[40:41], 0, v[38:39]
	global_load_dwordx4 v[22:25], v[22:23], off sc1 nt
	s_nop 0
	global_load_dwordx4 v[26:29], v[42:43], off sc1 nt
	global_load_dwordx4 v[30:33], v[44:45], off sc1 nt
	global_load_dwordx4 v[36:39], v[46:47], off sc1 nt
	s_nop 0
	global_load_dwordx4 v[40:43], v[48:49], off sc1 nt
	global_load_dwordx4 v[44:47], v[50:51], off sc1 nt
	s_nop 0
	global_load_dwordx4 v[48:51], v[52:53], off sc1 nt
	s_nop 0
	global_load_dwordx4 v[52:55], v[54:55], off sc1 nt
	v_add_u32_e32 v58, s4, v224
	v_add_u32_e32 v60, 8, v58
	v_add_u32_e32 v62, 16, v58
	v_add_u32_e32 v64, 24, v58
	s_ashr_i32 s1, s0, 31
	v_ashrrev_i32_e32 v59, 31, v58
	v_ashrrev_i32_e32 v61, 31, v60
	v_ashrrev_i32_e32 v63, 31, v62
	v_ashrrev_i32_e32 v65, 31, v64
	v_lshl_add_u64 v[56:57], s[0:1], 1, v[4:5]
	v_lshlrev_b64 v[58:59], 12, v[58:59]
	v_lshlrev_b64 v[60:61], 12, v[60:61]
	v_lshlrev_b64 v[62:63], 12, v[62:63]
	v_lshlrev_b64 v[64:65], 12, v[64:65]
	v_lshl_add_u64 v[58:59], v[56:57], 0, v[58:59]
	v_lshl_add_u64 v[60:61], v[56:57], 0, v[60:61]
	v_lshl_add_u64 v[62:63], v[56:57], 0, v[62:63]
	v_lshl_add_u64 v[56:57], v[56:57], 0, v[64:65]
	s_add_i32 s7, s7, s64
	s_add_i32 s3, s3, s6
	s_cmpk_lt_i32 s7, 0x800
	s_waitcnt vmcnt(7)
	ds_write2_b32 v6, v22, v23 offset1:1
	ds_write2_b32 v6, v24, v25 offset0:2 offset1:3
	s_waitcnt vmcnt(6)
	ds_write2_b32 v7, v26, v27 offset1:1
	ds_write2_b32 v8, v28, v29 offset1:1
	s_waitcnt vmcnt(5)
	ds_write2_b32 v9, v30, v31 offset1:1
	ds_write2_b32 v10, v32, v33 offset1:1
	s_waitcnt vmcnt(4)
	ds_write2_b32 v11, v36, v37 offset1:1
	ds_write2_b32 v12, v38, v39 offset1:1
	s_waitcnt vmcnt(3)
	ds_write2_b32 v13, v40, v41 offset1:1
	ds_write2_b32 v14, v42, v43 offset1:1
	s_waitcnt vmcnt(2)
	ds_write2_b32 v15, v44, v45 offset1:1
	ds_write2_b32 v16, v46, v47 offset1:1
	s_waitcnt vmcnt(1)
	ds_write2_b32 v17, v48, v49 offset1:1
	ds_write2_b32 v18, v50, v51 offset1:1
	s_waitcnt vmcnt(0)
	ds_write2_b32 v19, v52, v53 offset1:1
	ds_write2_b32 v20, v54, v55 offset1:1
	s_waitcnt lgkmcnt(0)
	ds_read2_b32 v[26:27], v1 offset0:33 offset1:41
	ds_read2_b32 v[28:29], v1 offset1:8
	ds_read2_b32 v[30:31], v1 offset0:66 offset1:74
	ds_read2_b32 v[32:33], v1 offset0:99 offset1:107
	ds_read2_b32 v[36:37], v1 offset0:132 offset1:140
	ds_read2_b32 v[38:39], v1 offset0:165 offset1:173
	ds_read2_b32 v[40:41], v1 offset0:198 offset1:206
	ds_read2_b32 v[42:43], v1 offset0:231 offset1:239
	ds_read2_b32 v[44:45], v1 offset0:49 offset1:57
	ds_read2_b32 v[46:47], v1 offset0:16 offset1:24
	ds_read2_b32 v[48:49], v1 offset0:82 offset1:90
	ds_read2_b32 v[50:51], v1 offset0:115 offset1:123
	ds_read2_b32 v[52:53], v1 offset0:148 offset1:156
	ds_read2_b32 v[54:55], v1 offset0:181 offset1:189
	ds_read2_b32 v[64:65], v1 offset0:214 offset1:222
	ds_read2_b32 v[66:67], v1 offset0:247 offset1:255
	s_waitcnt lgkmcnt(14)
	v_cvt_pk_bf16_f32 v22, v28, v26
	s_waitcnt lgkmcnt(12)
	v_cvt_pk_bf16_f32 v23, v30, v32
	s_waitcnt lgkmcnt(10)
	v_cvt_pk_bf16_f32 v24, v36, v38
	s_waitcnt lgkmcnt(8)
	v_cvt_pk_bf16_f32 v25, v40, v42
	v_cvt_pk_bf16_f32 v26, v29, v27
	v_cvt_pk_bf16_f32 v27, v31, v33
	v_cvt_pk_bf16_f32 v28, v37, v39
	v_cvt_pk_bf16_f32 v29, v41, v43
	s_waitcnt lgkmcnt(6)
	v_cvt_pk_bf16_f32 v30, v46, v44
	s_waitcnt lgkmcnt(4)
	v_cvt_pk_bf16_f32 v31, v48, v50
	s_waitcnt lgkmcnt(2)
	v_cvt_pk_bf16_f32 v32, v52, v54
	s_waitcnt lgkmcnt(0)
	v_cvt_pk_bf16_f32 v33, v64, v66
	v_cvt_pk_bf16_f32 v36, v47, v45
	v_cvt_pk_bf16_f32 v37, v49, v51
	v_cvt_pk_bf16_f32 v38, v53, v55
	v_cvt_pk_bf16_f32 v39, v65, v67
	global_store_dwordx4 v[58:59], v[22:25], off
	global_store_dwordx4 v[60:61], v[26:29], off
	global_store_dwordx4 v[62:63], v[30:33], off
	global_store_dwordx4 v[56:57], v[36:39], off
	s_waitcnt lgkmcnt(0)
	s_cbranch_scc1 .LBB0_54

; __device__ __forceinline__ void prep_rows_bf16(const float* X, float* rs, bf16* Hout, int gw, int NGW, int lane) {
;     for (int m = gw; m < M; m += NGW) { const f32x4* xr = (const f32x4*)(X + (size_t)m * DM) + lane; f32x4 v[8]; float s = 0.f;
; #pragma unroll
;         for (int j = 0; j < 8; ++j) { v[j] = xr[64 * j]; s += (v[j].x * v[j].x + v[j].y * v[j].y) + (v[j].z * v[j].z + v[j].w * v[j].w); }
;         const float rstd = 1.0f / sqrtf(wave_sum(s) * (1.f / DM) + EPS);
;         if (lane == 0) rs[m] = rstd;
.LBB0_69:
	global_load_dwordx4 v[6:9], v[36:37], off offset:-4096 sc1 nt
	global_load_dwordx4 v[2:5], v[36:37], off offset:-3072 sc1 nt
	global_load_dwordx4 v[10:13], v[36:37], off offset:-2048 sc1 nt
	global_load_dwordx4 v[14:17], v[36:37], off offset:-1024 sc1 nt
	global_load_dwordx4 v[18:21], v[36:37], off sc1 nt
	global_load_dwordx4 v[22:25], v[36:37], off offset:1024 sc1 nt
	global_load_dwordx4 v[26:29], v[36:37], off offset:2048 sc1 nt
	global_load_dwordx4 v[30:33], v[36:37], off offset:3072 sc1 nt
	s_waitcnt vmcnt(7)
	v_mul_f32_e32 v46, v7, v7
	v_mul_f32_e32 v47, v9, v9
	s_waitcnt vmcnt(6)
	v_mul_f32_e32 v48, v3, v3
	v_mul_f32_e32 v49, v5, v5
	s_waitcnt vmcnt(5)
	v_mul_f32_e32 v50, v11, v11
	v_mul_f32_e32 v51, v13, v13
	v_fmac_f32_e32 v46, v6, v6
	v_fmac_f32_e32 v47, v8, v8
	v_fmac_f32_e32 v48, v2, v2
	v_fmac_f32_e32 v49, v4, v4
	s_waitcnt vmcnt(4)
	v_mul_f32_e32 v52, v15, v15
	v_mul_f32_e32 v53, v17, v17
	v_fmac_f32_e32 v50, v10, v10
	v_fmac_f32_e32 v51, v12, v12
	v_add_f32_e32 v46, v46, v47
	v_add_f32_e32 v47, v48, v49
	s_waitcnt vmcnt(3)
	v_mul_f32_e32 v54, v19, v19
	v_mul_f32_e32 v55, v21, v21
	v_fmac_f32_e32 v52, v14, v14
	v_fmac_f32_e32 v53, v16, v16
	v_add_f32_e32 v48, v50, v51
	v_add_f32_e32 v46, v46, v47
	s_waitcnt vmcnt(2)
	v_mul_f32_e32 v56, v23, v23
	v_mul_f32_e32 v57, v25, v25
	v_fmac_f32_e32 v54, v18, v18
	v_fmac_f32_e32 v55, v20, v20
	v_add_f32_e32 v49, v52, v53
	v_add_f32_e32 v46, v46, v48
	s_waitcnt vmcnt(1)
	v_mul_f32_e32 v58, v27, v27
	v_mul_f32_e32 v59, v29, v29
	v_fmac_f32_e32 v56, v22, v22
	v_fmac_f32_e32 v57, v24, v24
	v_add_f32_e32 v50, v54, v55
	v_add_f32_e32 v46, v46, v49
	s_waitcnt vmcnt(0)
	v_mul_f32_e32 v60, v31, v31
	v_mul_f32_e32 v61, v33, v33
	v_fmac_f32_e32 v58, v26, v26
	v_fmac_f32_e32 v59, v28, v28
	v_add_f32_e32 v51, v56, v57
	v_add_f32_e32 v46, v46, v50
	v_fmac_f32_e32 v60, v30, v30
	v_fmac_f32_e32 v61, v32, v32
	v_add_f32_e32 v52, v58, v59
	v_add_f32_e32 v46, v46, v51
	v_add_f32_e32 v46, v46, v52
	v_add_f32_e32 v47, v60, v61
	v_add_f32_e32 v46, v46, v47
	ds_bpermute_b32 v47, v1, v46
	s_waitcnt lgkmcnt(0)
	v_add_f32_e32 v46, v46, v47
	ds_bpermute_b32 v47, v40, v46
	s_waitcnt lgkmcnt(0)
	v_add_f32_e32 v46, v46, v47
	ds_bpermute_b32 v47, v41, v46
	s_waitcnt lgkmcnt(0)
	v_add_f32_e32 v46, v46, v47
	ds_bpermute_b32 v47, v42, v46
	s_waitcnt lgkmcnt(0)
	v_add_f32_e32 v46, v46, v47
	ds_bpermute_b32 v47, v43, v46
	s_waitcnt lgkmcnt(0)
	v_add_f32_e32 v46, v46, v47
	ds_bpermute_b32 v47, v44, v46
	s_and_saveexec_b64 s[14:15], s[0:1]
	s_cbranch_execz .LBB0_68
	s_waitcnt lgkmcnt(0)
	v_add_f32_e32 v46, v46, v47
	v_fmamk_f32 v46, v46, 0x3a000000, v34
	v_mul_f32_e32 v47, 0x4f800000, v46
	v_cmp_gt_f32_e32 vcc, s21, v46
	s_nop 1
	v_cndmask_b32_e32 v46, v46, v47, vcc
	v_sqrt_f32_e32 v47, v46
	s_nop 0
	v_add_u32_e32 v48, -1, v47
	v_fma_f32 v50, -v48, v47, v46
	v_add_u32_e32 v49, 1, v47
	v_cmp_ge_f32_e64 s[6:7], 0, v50
	s_nop 1
	v_cndmask_b32_e64 v48, v47, v48, s[6:7]
	v_fma_f32 v47, -v49, v47, v46
	v_cmp_lt_f32_e64 s[6:7], 0, v47
	s_nop 1
	v_cndmask_b32_e64 v47, v48, v49, s[6:7]
	v_mul_f32_e32 v48, 0x37800000, v47
	v_cndmask_b32_e32 v47, v47, v48, vcc
	v_cmp_class_f32_e32 vcc, v46, v45
	s_nop 1
	v_cndmask_b32_e32 v46, v47, v46, vcc
	v_div_scale_f32 v47, s[6:7], v46, v46, 1.0
	v_rcp_f32_e32 v48, v47
	s_add_u32 s6, s62, s3
	s_addc_u32 s7, s63, s20
	v_fma_f32 v49, -v47, v48, 1.0
	v_fmac_f32_e32 v48, v49, v48
	v_div_scale_f32 v49, vcc, 1.0, v46, 1.0
	v_mul_f32_e32 v50, v49, v48
	v_fma_f32 v51, -v47, v50, v49
	v_fmac_f32_e32 v50, v51, v48
	v_fma_f32 v47, -v47, v50, v49
	v_div_fmas_f32 v47, v47, v48, v50
	v_div_fixup_f32 v46, v47, v46, 1.0
	global_store_dword v35, v46, s[6:7]
	s_branch .LBB0_68
